# grid barrier after the last layer's LN3 removed too (kernel ends right after it)
# speedup vs baseline: 1.0006x; 1.0006x over previous
; __global__ void __launch_bounds__(NT, 2) mk_fwd(Params P) {
;     ...
;             } else if (st == 3 || st == 9 || st == 12) {
;                 const float* lg = st == 3 ? P.in[2] : (st == 9 ? P.in[21] : P.in[25]); const float* lb = st == 3 ? P.in[3] : (st == 9 ? P.in[22] : P.in[26]);
;                 ln_pass(P, lg + l * DM, lb + l * DM, l == DEPTH - 1 && st == 12);
;     ...
;             if (l == 0 && st == 0) grid.sync();
;             xcd_barrier(xbar);
.LBB0_789:
	s_or_b64 exec, exec, s[26:27]
	s_mov_b32 s101, 0
	s_cmp_eq_u32 s76, 12
	s_cbranch_scc0 .Lln_noskip
	s_mov_b32 s101, 0x5a5a5a5a
